# reshead: P10/P13 residual rows of the first two epilogue groups are loaded before the K loop (registers v236-251 stay free across it)
# baseline (speedup 1.0000x reference)
.LBB0_1183:
	s_ashr_i32 s15, s14, 31
	v_cmp_lt_i64_e32 vcc, s[16:17], v[140:141]
	s_lshl_b64 s[16:17], s[14:15], 20
	s_add_u32 s16, s68, s16
	s_addc_u32 s17, s69, s17
	s_and_b64 s[18:19], vcc, exec
	s_cselect_b32 s15, s17, s25
	s_cselect_b32 s21, s16, s24
	s_ashr_i32 s13, s12, 31
	s_lshl_b64 s[18:19], s[12:13], 20
	s_add_u32 s18, s31, s18
	s_addc_u32 s19, s33, s19
	s_and_b64 s[28:29], vcc, exec
	s_cselect_b32 s13, s19, s27
	s_cselect_b32 s46, s18, s26
	s_add_u32 s24, s24, 0x80080
	s_addc_u32 s25, s25, 0
	s_add_u32 s47, s26, 0x100
	v_mov_b32_e32 v0, 0
	s_addc_u32 s48, s27, 0
	s_mov_b32 s49, -2
	s_waitcnt lgkmcnt(0)
	v_mov_b32_e32 v1, v0
	v_mov_b32_e32 v2, v0
	v_mov_b32_e32 v3, v0
	v_mov_b32_e32 v4, v0
	v_mov_b32_e32 v5, v0
	v_mov_b32_e32 v6, v0
	v_mov_b32_e32 v7, v0
	v_mov_b32_e32 v16, v0
	v_mov_b32_e32 v17, v0
	v_mov_b32_e32 v18, v0
	v_mov_b32_e32 v19, v0
	v_mov_b32_e32 v20, v0
	v_mov_b32_e32 v21, v0
	v_mov_b32_e32 v22, v0
	v_mov_b32_e32 v23, v0
	v_mov_b32_e32 v32, v0
	v_mov_b32_e32 v33, v0
	v_mov_b32_e32 v34, v0
	v_mov_b32_e32 v35, v0
	v_mov_b32_e32 v36, v0
	v_mov_b32_e32 v37, v0
	v_mov_b32_e32 v38, v0
	v_mov_b32_e32 v39, v0
	v_mov_b32_e32 v48, v0
	v_mov_b32_e32 v49, v0
	v_mov_b32_e32 v50, v0
	v_mov_b32_e32 v51, v0
	v_mov_b32_e32 v52, v0
	v_mov_b32_e32 v53, v0
	v_mov_b32_e32 v54, v0
	v_mov_b32_e32 v55, v0
	v_mov_b32_e32 v8, v0
	v_mov_b32_e32 v9, v0
	v_mov_b32_e32 v10, v0
	v_mov_b32_e32 v11, v0
	v_mov_b32_e32 v12, v0
	v_mov_b32_e32 v13, v0
	v_mov_b32_e32 v14, v0
	v_mov_b32_e32 v15, v0
	v_mov_b32_e32 v24, v0
	v_mov_b32_e32 v25, v0
	v_mov_b32_e32 v26, v0
	v_mov_b32_e32 v27, v0
	v_mov_b32_e32 v28, v0
	v_mov_b32_e32 v29, v0
	v_mov_b32_e32 v30, v0
	v_mov_b32_e32 v31, v0
	v_mov_b32_e32 v40, v0
	v_mov_b32_e32 v41, v0
	v_mov_b32_e32 v42, v0
	v_mov_b32_e32 v43, v0
	v_mov_b32_e32 v44, v0
	v_mov_b32_e32 v45, v0
	v_mov_b32_e32 v46, v0
	v_mov_b32_e32 v47, v0
	v_mov_b32_e32 v56, v0
	v_mov_b32_e32 v57, v0
	v_mov_b32_e32 v58, v0
	v_mov_b32_e32 v59, v0
	v_mov_b32_e32 v60, v0
	v_mov_b32_e32 v61, v0
	v_mov_b32_e32 v62, v0
	v_mov_b32_e32 v63, v0
	v_mov_b32_e32 v64, v0
	v_mov_b32_e32 v65, v0
	v_mov_b32_e32 v66, v0
	v_mov_b32_e32 v67, v0
	v_mov_b32_e32 v68, v0
	v_mov_b32_e32 v69, v0
	v_mov_b32_e32 v70, v0
	v_mov_b32_e32 v71, v0
	v_mov_b32_e32 v80, v0
	v_mov_b32_e32 v81, v0
	v_mov_b32_e32 v82, v0
	v_mov_b32_e32 v83, v0
	v_mov_b32_e32 v84, v0
	v_mov_b32_e32 v85, v0
	v_mov_b32_e32 v86, v0
	v_mov_b32_e32 v87, v0
	v_mov_b32_e32 v96, v0
	v_mov_b32_e32 v97, v0
	v_mov_b32_e32 v98, v0
	v_mov_b32_e32 v99, v0
	v_mov_b32_e32 v100, v0
	v_mov_b32_e32 v101, v0
	v_mov_b32_e32 v102, v0
	v_mov_b32_e32 v103, v0
	v_mov_b32_e32 v112, v0
	v_mov_b32_e32 v113, v0
	v_mov_b32_e32 v114, v0
	v_mov_b32_e32 v115, v0
	v_mov_b32_e32 v116, v0
	v_mov_b32_e32 v117, v0
	v_mov_b32_e32 v118, v0
	v_mov_b32_e32 v119, v0
	v_mov_b32_e32 v72, v0
	v_mov_b32_e32 v73, v0
	v_mov_b32_e32 v74, v0
	v_mov_b32_e32 v75, v0
	v_mov_b32_e32 v76, v0
	v_mov_b32_e32 v77, v0
	v_mov_b32_e32 v78, v0
	v_mov_b32_e32 v79, v0
	v_mov_b32_e32 v88, v0
	v_mov_b32_e32 v89, v0
	v_mov_b32_e32 v90, v0
	v_mov_b32_e32 v91, v0
	v_mov_b32_e32 v92, v0
	v_mov_b32_e32 v93, v0
	v_mov_b32_e32 v94, v0
	v_mov_b32_e32 v95, v0
	v_mov_b32_e32 v104, v0
	v_mov_b32_e32 v105, v0
	v_mov_b32_e32 v106, v0
	v_mov_b32_e32 v107, v0
	v_mov_b32_e32 v108, v0
	v_mov_b32_e32 v109, v0
	v_mov_b32_e32 v110, v0
	v_mov_b32_e32 v111, v0
	v_mov_b32_e32 v120, v0
	v_mov_b32_e32 v121, v0
	v_mov_b32_e32 v122, v0
	v_mov_b32_e32 v123, v0
	v_mov_b32_e32 v124, v0
	v_mov_b32_e32 v125, v0
	v_mov_b32_e32 v126, v0
	v_mov_b32_e32 v127, v0
	v_lshl_add_u32 v254, s20, 8, v148
	v_lshl_or_b32 v255, s22, 8, v150
	v_lshlrev_b32_e32 v254, 12, v254
	v_lshl_add_u32 v254, v255, 1, v254
	global_load_dwordx4 v[236:239], v254, s[6:7]
	global_load_dwordx4 v[240:243], v254, s[6:7] offset:256
	s_add_u32 s98, s6, 0x10000
	s_addc_u32 s99, s7, 0
	global_load_dwordx4 v[244:247], v254, s[98:99]
	global_load_dwordx4 v[248:251], v254, s[98:99] offset:256
.LBB0_1184:
	ds_read_b128 v[144:147], v151
	ds_read_b128 v[156:159], v151 offset:1024
	ds_read_b128 v[160:163], v151 offset:2048
	ds_read_b128 v[164:167], v151 offset:3072
	s_add_u32 s26, s24, 0xfff80080
	s_addc_u32 s27, s25, -1
	s_cmp_eq_u32 s49, 28
	s_cselect_b32 s29, s15, s27
	s_cselect_b32 s28, s21, s26
	s_cselect_b32 s27, s13, s48
	s_cselect_b32 s26, s46, s47
	v_lshl_add_u64 v[168:169], s[24:25], 0, v[136:137]
	s_add_i32 m0, s23, 0xc000
	ds_read_b128 v[172:175], v152
	ds_read_b128 v[176:179], v152 offset:1024
	ds_read_b128 v[180:183], v152 offset:2048
	ds_read_b128 v[184:187], v152 offset:3072
	ds_read_b128 v[188:191], v152 offset:4096
	ds_read_b128 v[192:195], v152 offset:5120
	ds_read_b128 v[196:199], v152 offset:6144
	ds_read_b128 v[200:203], v152 offset:7168
	global_load_lds_dwordx4 v[168:169], off
	v_lshl_add_u64 v[168:169], s[24:25], 0, v[138:139]
	s_add_i32 m0, s23, 0xe000
	s_nop 0
	global_load_lds_dwordx4 v[168:169], off
	s_waitcnt lgkmcnt(8)
	s_barrier
	s_waitcnt lgkmcnt(0)
	s_setprio 1
	s_waitcnt lgkmcnt(0)
	v_mfma_f32_16x16x32_bf16 v[124:127], v[144:147], v[172:175], v[124:127]
	v_mfma_f32_16x16x32_bf16 v[120:123], v[160:163], v[172:175], v[120:123]
	v_mfma_f32_16x16x32_bf16 v[108:111], v[144:147], v[180:183], v[108:111]
	v_mfma_f32_16x16x32_bf16 v[104:107], v[160:163], v[180:183], v[104:107]
	v_mfma_f32_16x16x32_bf16 v[92:95], v[144:147], v[188:191], v[92:95]
	v_mfma_f32_16x16x32_bf16 v[88:91], v[160:163], v[188:191], v[88:91]
	v_mfma_f32_16x16x32_bf16 v[76:79], v[144:147], v[196:199], v[76:79]
	v_mfma_f32_16x16x32_bf16 v[72:75], v[160:163], v[196:199], v[72:75]
	v_mfma_f32_16x16x32_bf16 v[124:127], v[156:159], v[176:179], v[124:127]
	v_mfma_f32_16x16x32_bf16 v[120:123], v[164:167], v[176:179], v[120:123]
	v_mfma_f32_16x16x32_bf16 v[108:111], v[156:159], v[184:187], v[108:111]
	v_mfma_f32_16x16x32_bf16 v[104:107], v[164:167], v[184:187], v[104:107]
	v_mfma_f32_16x16x32_bf16 v[92:95], v[156:159], v[192:195], v[92:95]
	v_mfma_f32_16x16x32_bf16 v[88:91], v[164:167], v[192:195], v[88:91]
	v_mfma_f32_16x16x32_bf16 v[76:79], v[156:159], v[200:203], v[76:79]
	v_mfma_f32_16x16x32_bf16 v[72:75], v[164:167], v[200:203], v[72:75]
	s_setprio 0
	s_barrier
	s_add_i32 s50, s44, s34
	v_lshl_add_u64 v[168:169], s[26:27], 0, v[130:131]
	s_mov_b32 m0, s50
	ds_read_b128 v[204:207], v153
	ds_read_b128 v[208:211], v153 offset:1024
	ds_read_b128 v[212:215], v153 offset:2048
	ds_read_b128 v[216:219], v153 offset:3072
	global_load_lds_dwordx4 v[168:169], off
	v_lshl_add_u64 v[220:221], s[26:27], 0, v[134:135]
	s_add_i32 m0, s50, 0x2000
	s_nop 0
	global_load_lds_dwordx4 v[220:221], off
	s_barrier
	s_waitcnt lgkmcnt(0)
	s_setprio 1
	s_waitcnt lgkmcnt(0)
	v_mfma_f32_16x16x32_bf16 v[116:119], v[204:207], v[172:175], v[116:119]
	v_mfma_f32_16x16x32_bf16 v[112:115], v[212:215], v[172:175], v[112:115]
	v_mfma_f32_16x16x32_bf16 v[100:103], v[204:207], v[180:183], v[100:103]
	v_mfma_f32_16x16x32_bf16 v[96:99], v[212:215], v[180:183], v[96:99]
	v_mfma_f32_16x16x32_bf16 v[84:87], v[204:207], v[188:191], v[84:87]
	v_mfma_f32_16x16x32_bf16 v[80:83], v[212:215], v[188:191], v[80:83]
	v_mfma_f32_16x16x32_bf16 v[68:71], v[204:207], v[196:199], v[68:71]
	v_mfma_f32_16x16x32_bf16 v[64:67], v[212:215], v[196:199], v[64:67]
	v_mfma_f32_16x16x32_bf16 v[116:119], v[208:211], v[176:179], v[116:119]
	v_mfma_f32_16x16x32_bf16 v[112:115], v[216:219], v[176:179], v[112:115]
	v_mfma_f32_16x16x32_bf16 v[100:103], v[208:211], v[184:187], v[100:103]
	v_mfma_f32_16x16x32_bf16 v[96:99], v[216:219], v[184:187], v[96:99]
	v_mfma_f32_16x16x32_bf16 v[84:87], v[208:211], v[192:195], v[84:87]
	v_mfma_f32_16x16x32_bf16 v[80:83], v[216:219], v[192:195], v[80:83]
	v_mfma_f32_16x16x32_bf16 v[68:71], v[208:211], v[200:203], v[68:71]
	v_mfma_f32_16x16x32_bf16 v[64:67], v[216:219], v[200:203], v[64:67]
	s_setprio 0
	s_mov_b32 m0, s23
	v_lshl_add_u64 v[222:223], s[28:29], 0, v[128:129]
	s_barrier
	ds_read_b128 v[172:175], v152 offset:16384
	ds_read_b128 v[176:179], v152 offset:17408
	ds_read_b128 v[180:183], v152 offset:18432
	ds_read_b128 v[184:187], v152 offset:19456
	ds_read_b128 v[188:191], v152 offset:20480
	ds_read_b128 v[192:195], v152 offset:21504
	ds_read_b128 v[196:199], v152 offset:22528
	ds_read_b128 v[200:203], v152 offset:23552
	global_load_lds_dwordx4 v[222:223], off
	v_lshl_add_u64 v[224:225], s[28:29], 0, v[132:133]
	s_mov_b32 m0, s35
	s_nop 0
	global_load_lds_dwordx4 v[224:225], off
	s_barrier
	s_waitcnt lgkmcnt(0)
	s_setprio 1
	s_waitcnt lgkmcnt(0)
	v_mfma_f32_16x16x32_bf16 v[60:63], v[144:147], v[172:175], v[60:63]
	v_mfma_f32_16x16x32_bf16 v[56:59], v[160:163], v[172:175], v[56:59]
	v_mfma_f32_16x16x32_bf16 v[44:47], v[144:147], v[180:183], v[44:47]
	v_mfma_f32_16x16x32_bf16 v[40:43], v[160:163], v[180:183], v[40:43]
	v_mfma_f32_16x16x32_bf16 v[28:31], v[144:147], v[188:191], v[28:31]
	v_mfma_f32_16x16x32_bf16 v[24:27], v[160:163], v[188:191], v[24:27]
	v_mfma_f32_16x16x32_bf16 v[12:15], v[144:147], v[196:199], v[12:15]
	v_mfma_f32_16x16x32_bf16 v[8:11], v[160:163], v[196:199], v[8:11]
	v_mfma_f32_16x16x32_bf16 v[60:63], v[156:159], v[176:179], v[60:63]
	v_mfma_f32_16x16x32_bf16 v[56:59], v[164:167], v[176:179], v[56:59]
	v_mfma_f32_16x16x32_bf16 v[44:47], v[156:159], v[184:187], v[44:47]
	v_mfma_f32_16x16x32_bf16 v[40:43], v[164:167], v[184:187], v[40:43]
	v_mfma_f32_16x16x32_bf16 v[28:31], v[156:159], v[192:195], v[28:31]
	v_mfma_f32_16x16x32_bf16 v[24:27], v[164:167], v[192:195], v[24:27]
	v_mfma_f32_16x16x32_bf16 v[12:15], v[156:159], v[200:203], v[12:15]
	v_mfma_f32_16x16x32_bf16 v[8:11], v[164:167], v[200:203], v[8:11]
	s_setprio 0
	s_barrier
	s_add_u32 s50, s26, 0x80000
	s_addc_u32 s51, s27, 0
	s_add_i32 s52, s45, s34
	v_lshl_add_u64 v[144:145], s[50:51], 0, v[130:131]
	s_mov_b32 m0, s52
	s_nop 0
	global_load_lds_dwordx4 v[144:145], off
	v_lshl_add_u64 v[144:145], s[50:51], 0, v[134:135]
	s_add_i32 m0, s52, 0x2000
	s_nop 0
	global_load_lds_dwordx4 v[144:145], off
	s_waitcnt vmcnt(6)
	s_barrier
	s_setprio 1
	v_mfma_f32_16x16x32_bf16 v[52:55], v[204:207], v[172:175], v[52:55]
	v_mfma_f32_16x16x32_bf16 v[48:51], v[212:215], v[172:175], v[48:51]
	v_mfma_f32_16x16x32_bf16 v[36:39], v[204:207], v[180:183], v[36:39]
	v_mfma_f32_16x16x32_bf16 v[32:35], v[212:215], v[180:183], v[32:35]
	v_mfma_f32_16x16x32_bf16 v[20:23], v[204:207], v[188:191], v[20:23]
	v_mfma_f32_16x16x32_bf16 v[16:19], v[212:215], v[188:191], v[16:19]
	v_mfma_f32_16x16x32_bf16 v[4:7], v[204:207], v[196:199], v[4:7]
	v_mfma_f32_16x16x32_bf16 v[0:3], v[212:215], v[196:199], v[0:3]
	v_mfma_f32_16x16x32_bf16 v[52:55], v[208:211], v[176:179], v[52:55]
	v_mfma_f32_16x16x32_bf16 v[48:51], v[216:219], v[176:179], v[48:51]
	v_mfma_f32_16x16x32_bf16 v[36:39], v[208:211], v[184:187], v[36:39]
	v_mfma_f32_16x16x32_bf16 v[32:35], v[216:219], v[184:187], v[32:35]
	v_mfma_f32_16x16x32_bf16 v[20:23], v[208:211], v[192:195], v[20:23]
	v_mfma_f32_16x16x32_bf16 v[16:19], v[216:219], v[192:195], v[16:19]
	v_mfma_f32_16x16x32_bf16 v[4:7], v[208:211], v[200:203], v[4:7]
	v_mfma_f32_16x16x32_bf16 v[0:3], v[216:219], v[200:203], v[0:3]
	s_setprio 0
	s_add_i32 s50, 0, 0x18000
	v_add_u32_e32 v155, s50, v149
	s_barrier
	ds_read_b128 v[144:147], v155
	ds_read_b128 v[156:159], v155 offset:1024
	ds_read_b128 v[160:163], v155 offset:2048
	ds_read_b128 v[164:167], v155 offset:3072
	s_add_u32 s28, s28, 0x80000
	s_addc_u32 s29, s29, 0
	s_mov_b32 m0, s36
	v_lshl_add_u64 v[204:205], s[28:29], 0, v[128:129]
	ds_read_b128 v[172:175], v152 offset:32768
	ds_read_b128 v[176:179], v152 offset:33792
	ds_read_b128 v[180:183], v152 offset:34816
	ds_read_b128 v[184:187], v152 offset:35840
	ds_read_b128 v[188:191], v152 offset:36864
	ds_read_b128 v[192:195], v152 offset:37888
	ds_read_b128 v[196:199], v152 offset:38912
	ds_read_b128 v[200:203], v152 offset:39936
	global_load_lds_dwordx4 v[204:205], off
	v_lshl_add_u64 v[204:205], s[28:29], 0, v[132:133]
	s_mov_b32 m0, s37
	s_nop 0
	global_load_lds_dwordx4 v[204:205], off
	s_waitcnt lgkmcnt(8)
	s_barrier
	s_waitcnt lgkmcnt(0)
	s_setprio 1
	s_waitcnt lgkmcnt(0)
	v_mfma_f32_16x16x32_bf16 v[124:127], v[144:147], v[172:175], v[124:127]
	v_mfma_f32_16x16x32_bf16 v[120:123], v[160:163], v[172:175], v[120:123]
	v_mfma_f32_16x16x32_bf16 v[108:111], v[144:147], v[180:183], v[108:111]
	v_mfma_f32_16x16x32_bf16 v[104:107], v[160:163], v[180:183], v[104:107]
	v_mfma_f32_16x16x32_bf16 v[92:95], v[144:147], v[188:191], v[92:95]
	v_mfma_f32_16x16x32_bf16 v[88:91], v[160:163], v[188:191], v[88:91]
	v_mfma_f32_16x16x32_bf16 v[76:79], v[144:147], v[196:199], v[76:79]
	v_mfma_f32_16x16x32_bf16 v[72:75], v[160:163], v[196:199], v[72:75]
	v_mfma_f32_16x16x32_bf16 v[124:127], v[156:159], v[176:179], v[124:127]
	v_mfma_f32_16x16x32_bf16 v[120:123], v[164:167], v[176:179], v[120:123]
	v_mfma_f32_16x16x32_bf16 v[108:111], v[156:159], v[184:187], v[108:111]
	v_mfma_f32_16x16x32_bf16 v[104:107], v[164:167], v[184:187], v[104:107]
	v_mfma_f32_16x16x32_bf16 v[92:95], v[156:159], v[192:195], v[92:95]
	v_mfma_f32_16x16x32_bf16 v[88:91], v[164:167], v[192:195], v[88:91]
	v_mfma_f32_16x16x32_bf16 v[76:79], v[156:159], v[200:203], v[76:79]
	v_mfma_f32_16x16x32_bf16 v[72:75], v[164:167], v[200:203], v[72:75]
	s_setprio 0
	s_barrier
	s_add_i32 s28, 0, 0x1c000
	s_add_i32 s29, s50, s34
	v_add_u32_e32 v155, s28, v149
	v_lshl_add_u64 v[168:169], v[168:169], 0, s[10:11]
	s_mov_b32 m0, s29
	ds_read_b128 v[204:207], v155
	ds_read_b128 v[208:211], v155 offset:1024
	ds_read_b128 v[212:215], v155 offset:2048
	ds_read_b128 v[216:219], v155 offset:3072
	global_load_lds_dwordx4 v[168:169], off
	v_lshl_add_u64 v[168:169], v[220:221], 0, s[10:11]
	s_add_i32 m0, s29, 0x2000
	s_nop 0
	global_load_lds_dwordx4 v[168:169], off
	s_barrier
	s_waitcnt lgkmcnt(0)
	s_setprio 1
	s_waitcnt lgkmcnt(0)
	v_mfma_f32_16x16x32_bf16 v[116:119], v[204:207], v[172:175], v[116:119]
	v_mfma_f32_16x16x32_bf16 v[112:115], v[212:215], v[172:175], v[112:115]
	v_mfma_f32_16x16x32_bf16 v[100:103], v[204:207], v[180:183], v[100:103]
	v_mfma_f32_16x16x32_bf16 v[96:99], v[212:215], v[180:183], v[96:99]
	v_mfma_f32_16x16x32_bf16 v[84:87], v[204:207], v[188:191], v[84:87]
	v_mfma_f32_16x16x32_bf16 v[80:83], v[212:215], v[188:191], v[80:83]
	v_mfma_f32_16x16x32_bf16 v[68:71], v[204:207], v[196:199], v[68:71]
	v_mfma_f32_16x16x32_bf16 v[64:67], v[212:215], v[196:199], v[64:67]
	v_mfma_f32_16x16x32_bf16 v[116:119], v[208:211], v[176:179], v[116:119]
	v_mfma_f32_16x16x32_bf16 v[112:115], v[216:219], v[176:179], v[112:115]
	v_mfma_f32_16x16x32_bf16 v[100:103], v[208:211], v[184:187], v[100:103]
	v_mfma_f32_16x16x32_bf16 v[96:99], v[216:219], v[184:187], v[96:99]
	v_mfma_f32_16x16x32_bf16 v[84:87], v[208:211], v[192:195], v[84:87]
	v_mfma_f32_16x16x32_bf16 v[80:83], v[216:219], v[192:195], v[80:83]
	v_mfma_f32_16x16x32_bf16 v[68:71], v[208:211], v[200:203], v[68:71]
	v_mfma_f32_16x16x32_bf16 v[64:67], v[216:219], v[200:203], v[64:67]
	s_setprio 0
	s_mov_b32 m0, s39
	v_lshl_add_u64 v[168:169], v[222:223], 0, s[10:11]
	s_barrier
	ds_read_b128 v[172:175], v152 offset:49152
	ds_read_b128 v[176:179], v152 offset:50176
	ds_read_b128 v[180:183], v152 offset:51200
	ds_read_b128 v[184:187], v152 offset:52224
	ds_read_b128 v[188:191], v152 offset:53248
	ds_read_b128 v[192:195], v152 offset:54272
	ds_read_b128 v[196:199], v152 offset:55296
	ds_read_b128 v[200:203], v152 offset:56320
	global_load_lds_dwordx4 v[168:169], off
	v_lshl_add_u64 v[168:169], v[224:225], 0, s[10:11]
	s_mov_b32 m0, s40
	s_nop 0
	global_load_lds_dwordx4 v[168:169], off
	s_barrier
	s_waitcnt lgkmcnt(0)
	s_setprio 1
	s_waitcnt lgkmcnt(0)
	v_mfma_f32_16x16x32_bf16 v[60:63], v[144:147], v[172:175], v[60:63]
	v_mfma_f32_16x16x32_bf16 v[56:59], v[160:163], v[172:175], v[56:59]
	v_mfma_f32_16x16x32_bf16 v[44:47], v[144:147], v[180:183], v[44:47]
	v_mfma_f32_16x16x32_bf16 v[40:43], v[160:163], v[180:183], v[40:43]
	v_mfma_f32_16x16x32_bf16 v[28:31], v[144:147], v[188:191], v[28:31]
	v_mfma_f32_16x16x32_bf16 v[24:27], v[160:163], v[188:191], v[24:27]
	v_mfma_f32_16x16x32_bf16 v[12:15], v[144:147], v[196:199], v[12:15]
	v_mfma_f32_16x16x32_bf16 v[8:11], v[160:163], v[196:199], v[8:11]
	v_mfma_f32_16x16x32_bf16 v[60:63], v[156:159], v[176:179], v[60:63]
	v_mfma_f32_16x16x32_bf16 v[56:59], v[164:167], v[176:179], v[56:59]
	v_mfma_f32_16x16x32_bf16 v[44:47], v[156:159], v[184:187], v[44:47]
	v_mfma_f32_16x16x32_bf16 v[40:43], v[164:167], v[184:187], v[40:43]
	v_mfma_f32_16x16x32_bf16 v[28:31], v[156:159], v[192:195], v[28:31]
	v_mfma_f32_16x16x32_bf16 v[24:27], v[164:167], v[192:195], v[24:27]
	v_mfma_f32_16x16x32_bf16 v[12:15], v[156:159], v[200:203], v[12:15]
	v_mfma_f32_16x16x32_bf16 v[8:11], v[164:167], v[200:203], v[8:11]
	s_setprio 0
	s_barrier
	s_add_u32 s26, s26, 0x80080
	s_addc_u32 s27, s27, 0
	s_add_i32 s28, s28, s34
	v_lshl_add_u64 v[144:145], s[26:27], 0, v[130:131]
	s_mov_b32 m0, s28
	s_nop 0
	global_load_lds_dwordx4 v[144:145], off
	v_lshl_add_u64 v[144:145], s[26:27], 0, v[134:135]
	s_add_i32 m0, s28, 0x2000
	s_nop 0
	global_load_lds_dwordx4 v[144:145], off
	s_waitcnt vmcnt(6)
	s_barrier
	s_setprio 1
	v_mfma_f32_16x16x32_bf16 v[52:55], v[204:207], v[172:175], v[52:55]
	v_mfma_f32_16x16x32_bf16 v[48:51], v[212:215], v[172:175], v[48:51]
	v_mfma_f32_16x16x32_bf16 v[36:39], v[204:207], v[180:183], v[36:39]
	v_mfma_f32_16x16x32_bf16 v[32:35], v[212:215], v[180:183], v[32:35]
	v_mfma_f32_16x16x32_bf16 v[20:23], v[204:207], v[188:191], v[20:23]
	v_mfma_f32_16x16x32_bf16 v[16:19], v[212:215], v[188:191], v[16:19]
	v_mfma_f32_16x16x32_bf16 v[4:7], v[204:207], v[196:199], v[4:7]
	v_mfma_f32_16x16x32_bf16 v[0:3], v[212:215], v[196:199], v[0:3]
	v_mfma_f32_16x16x32_bf16 v[52:55], v[208:211], v[176:179], v[52:55]
	v_mfma_f32_16x16x32_bf16 v[48:51], v[216:219], v[176:179], v[48:51]
	v_mfma_f32_16x16x32_bf16 v[36:39], v[208:211], v[184:187], v[36:39]
	v_mfma_f32_16x16x32_bf16 v[32:35], v[216:219], v[184:187], v[32:35]
	v_mfma_f32_16x16x32_bf16 v[20:23], v[208:211], v[192:195], v[20:23]
	v_mfma_f32_16x16x32_bf16 v[16:19], v[216:219], v[192:195], v[16:19]
	v_mfma_f32_16x16x32_bf16 v[4:7], v[208:211], v[200:203], v[4:7]
	v_mfma_f32_16x16x32_bf16 v[0:3], v[216:219], v[200:203], v[0:3]
	s_setprio 0
	s_add_i32 s49, s49, 2
	s_add_u32 s24, s24, 0x100
	s_addc_u32 s25, s25, 0
	s_add_u32 s47, s47, 0x100
	s_addc_u32 s48, s48, 0
	s_cmp_gt_u32 s49, 29
	s_barrier
	s_cbranch_scc0 .LBB0_1184
	v_lshl_add_u32 v146, s20, 8, v148
	v_ashrrev_i32_e32 v147, 31, v146
	v_lshl_or_b32 v144, s22, 8, v150
	v_lshlrev_b32_e32 v179, 12, v146
	v_lshl_add_u32 v178, v144, 1, v179
	s_add_u32 s98, s6, 0x20000
	s_addc_u32 s99, s7, 0
	global_load_dwordx4 v[196:199], v178, s[98:99]
	global_load_dwordx4 v[200:203], v178, s[98:99] offset:256
	s_add_u32 s98, s6, 0x30000
	s_addc_u32 s99, s7, 0
	global_load_dwordx4 v[204:207], v178, s[98:99]
	global_load_dwordx4 v[208:211], v178, s[98:99] offset:256
	s_add_u32 s98, s6, 0x80000
	s_addc_u32 s99, s7, 0
	global_load_dwordx4 v[212:215], v178, s[98:99]
	global_load_dwordx4 v[216:219], v178, s[98:99] offset:256
	s_add_u32 s98, s6, 0x90000
	s_addc_u32 s99, s7, 0
	global_load_dwordx4 v[180:183], v178, s[98:99]
	global_load_dwordx4 v[184:187], v178, s[98:99] offset:256
	s_add_u32 s98, s6, 0xa0000
	s_addc_u32 s99, s7, 0
	global_load_dwordx4 v[188:191], v178, s[98:99]
	global_load_dwordx4 v[192:195], v178, s[98:99] offset:256
	s_add_u32 s98, s6, 0xb0000
	s_addc_u32 s99, s7, 0
	global_load_dwordx4 v[220:223], v178, s[98:99]
	global_load_dwordx4 v[252:255], v178, s[98:99] offset:256
	v_lshlrev_b64 v[156:157], 12, v[146:147]
	v_ashrrev_i32_e32 v145, 31, v144
	v_lshl_add_u64 v[156:157], s[6:7], 0, v[156:157]
	v_lshl_add_u64 v[166:167], v[144:145], 1, v[156:157]
	v_and_b32_e32 v156, 64, v154
	v_xor_b32_e32 v155, 16, v154
	v_add_u32_e32 v156, 64, v156
	v_xor_b32_e32 v157, 32, v154
	v_cmp_lt_i32_e32 vcc, v155, v156
	s_waitcnt vmcnt(12)
	v_lshlrev_b32_e32 v168, 16, v236
	v_and_b32_e32 v169, 0xffff0000, v236
	v_lshlrev_b32_e32 v236, 16, v237
	v_and_b32_e32 v237, 0xffff0000, v237
	v_lshlrev_b32_e32 v174, 16, v240
	v_and_b32_e32 v175, 0xffff0000, v240
	v_lshlrev_b32_e32 v240, 16, v241
	v_and_b32_e32 v241, 0xffff0000, v241
	v_cndmask_b32_e32 v155, v154, v155, vcc
	v_cmp_lt_i32_e32 vcc, v157, v156
	v_lshlrev_b32_e32 v172, 16, v238
	v_and_b32_e32 v173, 0xffff0000, v238
	v_lshlrev_b32_e32 v238, 16, v239
	v_and_b32_e32 v239, 0xffff0000, v239
	v_lshlrev_b32_e32 v176, 16, v242
	v_and_b32_e32 v177, 0xffff0000, v242
	v_lshlrev_b32_e32 v242, 16, v243
	v_and_b32_e32 v243, 0xffff0000, v243
	v_pk_add_f32 v[126:127], v[126:127], v[236:237]
	v_pk_add_f32 v[124:125], v[124:125], v[168:169]
	v_pk_add_f32 v[118:119], v[118:119], v[240:241]
	v_pk_add_f32 v[116:117], v[116:117], v[174:175]
	v_cndmask_b32_e32 v157, v154, v157, vcc
	v_pk_add_f32 v[122:123], v[122:123], v[238:239]
	v_pk_add_f32 v[120:121], v[120:121], v[172:173]
	v_pk_add_f32 v[236:237], v[114:115], v[242:243]
	v_pk_add_f32 v[238:239], v[112:113], v[176:177]
	v_mul_f32_e32 v114, v125, v125
	v_mul_f32_e32 v115, v127, v127
	v_cvt_pk_bf16_f32 v112, v124, v125
	v_cvt_pk_bf16_f32 v113, v126, v127
	v_mul_f32_e32 v125, v117, v117
	v_mul_f32_e32 v127, v119, v119
	v_lshlrev_b32_e32 v156, 2, v155
	v_lshlrev_b32_e32 v155, 2, v157
	v_mul_f32_e32 v157, v121, v121
	v_mul_f32_e32 v241, v239, v239
	v_fmac_f32_e32 v114, v124, v124
	v_fmac_f32_e32 v115, v126, v126
	v_fmac_f32_e32 v125, v116, v116
	v_fmac_f32_e32 v127, v118, v118
	v_mul_f32_e32 v240, v123, v123
	v_mul_f32_e32 v242, v237, v237
	v_fmac_f32_e32 v157, v120, v120
	v_fmac_f32_e32 v241, v238, v238
	v_add_f32_e32 v114, v114, v115
	v_add_f32_e32 v115, v125, v127
	v_fmac_f32_e32 v240, v122, v122
	v_fmac_f32_e32 v242, v236, v236
	v_add_f32_e32 v114, v157, v114
	v_add_f32_e32 v115, v241, v115
	v_add_f32_e32 v114, v240, v114
	v_add_f32_e32 v115, v242, v115
	v_add_f32_e32 v124, v114, v115
	ds_bpermute_b32 v125, v156, v124
	v_cvt_pk_bf16_f32 v114, v120, v121
	v_cvt_pk_bf16_f32 v115, v122, v123
	global_store_dwordx4 v[166:167], v[112:115], off
	s_waitcnt lgkmcnt(0)
	s_nop 0
	v_add_f32_e32 v112, v124, v125
	ds_bpermute_b32 v113, v155, v112
	v_cvt_pk_bf16_f32 v114, v116, v117
	v_cvt_pk_bf16_f32 v115, v118, v119
	v_cvt_pk_bf16_f32 v116, v238, v239
	v_cvt_pk_bf16_f32 v117, v236, v237
	global_store_dwordx4 v[166:167], v[114:117], off offset:256
	s_and_saveexec_b64 s[20:21], s[2:3]
	s_cbranch_execz .LBB0_1187
	v_lshl_add_u64 v[114:115], v[146:147], 2, s[8:9]
	s_waitcnt lgkmcnt(0)
	v_add_f32_e32 v112, v112, v113
	global_atomic_add_f32 v[114:115], v112, off
.LBB0_1187:
	s_or_b64 exec, exec, s[20:21]
	v_or_b32_e32 v112, 16, v146
	s_waitcnt lgkmcnt(0)
	v_ashrrev_i32_e32 v113, 31, v112
	v_lshlrev_b64 v[114:115], 12, v[112:113]
	v_lshl_add_u64 v[114:115], s[6:7], 0, v[114:115]
	v_lshl_add_u64 v[122:123], v[144:145], 1, v[114:115]
	s_waitcnt vmcnt(15)
	v_lshlrev_b32_e32 v124, 16, v244
	v_and_b32_e32 v125, 0xffff0000, v244
	v_lshlrev_b32_e32 v244, 16, v245
	v_and_b32_e32 v245, 0xffff0000, v245
	s_waitcnt vmcnt(15)
	v_lshlrev_b32_e32 v158, 16, v248
	v_and_b32_e32 v159, 0xffff0000, v248
	v_lshlrev_b32_e32 v248, 16, v249
	v_and_b32_e32 v249, 0xffff0000, v249
	v_lshlrev_b32_e32 v126, 16, v246
	v_and_b32_e32 v127, 0xffff0000, v246
	v_lshlrev_b32_e32 v246, 16, v247
	v_and_b32_e32 v247, 0xffff0000, v247
	v_lshlrev_b32_e32 v160, 16, v250
	v_and_b32_e32 v161, 0xffff0000, v250
	v_lshlrev_b32_e32 v250, 16, v251
	v_and_b32_e32 v251, 0xffff0000, v251
	v_pk_add_f32 v[110:111], v[110:111], v[244:245]
	v_pk_add_f32 v[108:109], v[108:109], v[124:125]
	v_pk_add_f32 v[102:103], v[102:103], v[248:249]
	v_pk_add_f32 v[100:101], v[100:101], v[158:159]
	v_pk_add_f32 v[106:107], v[106:107], v[246:247]
	v_pk_add_f32 v[104:105], v[104:105], v[126:127]
	v_pk_add_f32 v[244:245], v[98:99], v[250:251]
	v_pk_add_f32 v[246:247], v[96:97], v[160:161]
	v_mul_f32_e32 v98, v109, v109
	v_mul_f32_e32 v99, v111, v111
	v_cvt_pk_bf16_f32 v96, v108, v109
	v_cvt_pk_bf16_f32 v97, v110, v111
	v_mul_f32_e32 v109, v101, v101
	v_mul_f32_e32 v111, v103, v103
	v_mul_f32_e32 v248, v105, v105
	v_mul_f32_e32 v250, v247, v247
	v_fmac_f32_e32 v98, v108, v108
	v_fmac_f32_e32 v99, v110, v110
	v_fmac_f32_e32 v109, v100, v100
	v_fmac_f32_e32 v111, v102, v102
	v_mul_f32_e32 v249, v107, v107
	v_mul_f32_e32 v251, v245, v245
	v_fmac_f32_e32 v248, v104, v104
	v_fmac_f32_e32 v250, v246, v246
	v_add_f32_e32 v98, v98, v99
	v_add_f32_e32 v99, v109, v111
	v_fmac_f32_e32 v249, v106, v106
	v_fmac_f32_e32 v251, v244, v244
	v_add_f32_e32 v98, v248, v98
	v_add_f32_e32 v99, v250, v99
	v_add_f32_e32 v98, v249, v98
	v_add_f32_e32 v99, v251, v99
	v_add_f32_e32 v108, v98, v99
	ds_bpermute_b32 v109, v156, v108
	v_cvt_pk_bf16_f32 v98, v104, v105
	v_cvt_pk_bf16_f32 v99, v106, v107
	global_store_dwordx4 v[122:123], v[96:99], off
	s_waitcnt lgkmcnt(0)
	s_nop 0
	v_add_f32_e32 v96, v108, v109
	ds_bpermute_b32 v97, v155, v96
	v_cvt_pk_bf16_f32 v98, v100, v101
	v_cvt_pk_bf16_f32 v99, v102, v103
	v_cvt_pk_bf16_f32 v100, v246, v247
	v_cvt_pk_bf16_f32 v101, v244, v245
	global_store_dwordx4 v[122:123], v[98:101], off offset:256
	s_and_saveexec_b64 s[20:21], s[2:3]
	s_cbranch_execz .LBB0_1189
	v_lshl_add_u64 v[98:99], v[112:113], 2, s[8:9]
	s_waitcnt lgkmcnt(0)
	v_add_f32_e32 v96, v96, v97
	global_atomic_add_f32 v[98:99], v96, off

.LBB0_1195:
	s_or_b64 exec, exec, s[20:21]
	v_add_u32_e32 v48, 0x90, v146
	s_waitcnt lgkmcnt(0)
	v_ashrrev_i32_e32 v49, 31, v48
	v_lshlrev_b64 v[50:51], 12, v[48:49]
	v_lshl_add_u64 v[50:51], s[6:7], 0, v[50:51]
	v_lshl_add_u64 v[58:59], v[144:145], 1, v[50:51]
	s_waitcnt vmcnt(20)
	v_lshlrev_b32_e32 v60, 16, v180
	v_and_b32_e32 v61, 0xffff0000, v180
	v_lshlrev_b32_e32 v180, 16, v181
	v_and_b32_e32 v181, 0xffff0000, v181
	s_waitcnt vmcnt(19)
	v_lshlrev_b32_e32 v64, 16, v184
	v_and_b32_e32 v65, 0xffff0000, v184
	v_lshlrev_b32_e32 v184, 16, v185
	v_and_b32_e32 v185, 0xffff0000, v185
	v_lshlrev_b32_e32 v62, 16, v182
	v_and_b32_e32 v63, 0xffff0000, v182
	v_lshlrev_b32_e32 v182, 16, v183
	v_and_b32_e32 v183, 0xffff0000, v183
	v_lshlrev_b32_e32 v66, 16, v186
	v_and_b32_e32 v67, 0xffff0000, v186
	v_lshlrev_b32_e32 v186, 16, v187
	v_and_b32_e32 v187, 0xffff0000, v187
	v_pk_add_f32 v[46:47], v[46:47], v[180:181]
	v_pk_add_f32 v[44:45], v[44:45], v[60:61]
	v_pk_add_f32 v[38:39], v[38:39], v[184:185]
	v_pk_add_f32 v[36:37], v[36:37], v[64:65]
	v_pk_add_f32 v[42:43], v[42:43], v[182:183]
	v_pk_add_f32 v[40:41], v[40:41], v[62:63]
	v_pk_add_f32 v[180:181], v[34:35], v[186:187]
	v_pk_add_f32 v[182:183], v[32:33], v[66:67]
	v_mul_f32_e32 v34, v45, v45
	v_mul_f32_e32 v35, v47, v47
	v_cvt_pk_bf16_f32 v32, v44, v45
	v_cvt_pk_bf16_f32 v33, v46, v47
	v_mul_f32_e32 v45, v37, v37
	v_mul_f32_e32 v47, v39, v39
	v_mul_f32_e32 v184, v41, v41
	v_mul_f32_e32 v186, v183, v183
	v_fmac_f32_e32 v34, v44, v44
	v_fmac_f32_e32 v35, v46, v46
	v_fmac_f32_e32 v45, v36, v36
	v_fmac_f32_e32 v47, v38, v38
	v_mul_f32_e32 v185, v43, v43
	v_mul_f32_e32 v187, v181, v181
	v_fmac_f32_e32 v184, v40, v40
	v_fmac_f32_e32 v186, v182, v182
	v_add_f32_e32 v34, v34, v35
	v_add_f32_e32 v35, v45, v47
	v_fmac_f32_e32 v185, v42, v42
	v_fmac_f32_e32 v187, v180, v180
	v_add_f32_e32 v34, v184, v34
	v_add_f32_e32 v35, v186, v35
	v_add_f32_e32 v34, v185, v34
	v_add_f32_e32 v35, v187, v35
	v_add_f32_e32 v44, v34, v35
	ds_bpermute_b32 v45, v156, v44
	v_cvt_pk_bf16_f32 v34, v40, v41
	v_cvt_pk_bf16_f32 v35, v42, v43
	global_store_dwordx4 v[58:59], v[32:35], off
	s_waitcnt lgkmcnt(0)
	s_nop 0
	v_add_f32_e32 v32, v44, v45
	ds_bpermute_b32 v33, v155, v32
	v_cvt_pk_bf16_f32 v34, v36, v37
	v_cvt_pk_bf16_f32 v35, v38, v39
	v_cvt_pk_bf16_f32 v36, v182, v183
	v_cvt_pk_bf16_f32 v37, v180, v181
	global_store_dwordx4 v[58:59], v[34:37], off offset:256
	s_and_saveexec_b64 s[20:21], s[2:3]
	s_cbranch_execz .LBB0_1197
	v_lshl_add_u64 v[34:35], v[48:49], 2, s[8:9]
	s_waitcnt lgkmcnt(0)
	v_add_f32_e32 v32, v32, v33
	global_atomic_add_f32 v[34:35], v32, off
.LBB0_1197:
	s_or_b64 exec, exec, s[20:21]
	v_add_u32_e32 v32, 0xa0, v146
	s_waitcnt lgkmcnt(0)
	v_ashrrev_i32_e32 v33, 31, v32
	v_lshlrev_b64 v[34:35], 12, v[32:33]
	v_lshl_add_u64 v[34:35], s[6:7], 0, v[34:35]
	v_lshl_add_u64 v[42:43], v[144:145], 1, v[34:35]
	s_waitcnt vmcnt(21)
	v_lshlrev_b32_e32 v44, 16, v188
	v_and_b32_e32 v45, 0xffff0000, v188
	v_lshlrev_b32_e32 v188, 16, v189
	v_and_b32_e32 v189, 0xffff0000, v189
	s_waitcnt vmcnt(20)
	v_lshlrev_b32_e32 v48, 16, v192
	v_and_b32_e32 v49, 0xffff0000, v192
	v_lshlrev_b32_e32 v192, 16, v193
	v_and_b32_e32 v193, 0xffff0000, v193
	v_lshlrev_b32_e32 v46, 16, v190
	v_and_b32_e32 v47, 0xffff0000, v190
	v_lshlrev_b32_e32 v190, 16, v191
	v_and_b32_e32 v191, 0xffff0000, v191
	v_lshlrev_b32_e32 v50, 16, v194
	v_and_b32_e32 v51, 0xffff0000, v194
	v_lshlrev_b32_e32 v194, 16, v195
	v_and_b32_e32 v195, 0xffff0000, v195
	v_pk_add_f32 v[30:31], v[30:31], v[188:189]
	v_pk_add_f32 v[28:29], v[28:29], v[44:45]
	v_pk_add_f32 v[22:23], v[22:23], v[192:193]
	v_pk_add_f32 v[20:21], v[20:21], v[48:49]
	v_pk_add_f32 v[26:27], v[26:27], v[190:191]
	v_pk_add_f32 v[24:25], v[24:25], v[46:47]
	v_pk_add_f32 v[188:189], v[18:19], v[194:195]
	v_pk_add_f32 v[190:191], v[16:17], v[50:51]
	v_mul_f32_e32 v18, v29, v29
	v_mul_f32_e32 v19, v31, v31
	v_cvt_pk_bf16_f32 v16, v28, v29
	v_cvt_pk_bf16_f32 v17, v30, v31
	v_mul_f32_e32 v29, v21, v21
	v_mul_f32_e32 v31, v23, v23
	v_mul_f32_e32 v192, v25, v25
	v_mul_f32_e32 v194, v191, v191
	v_fmac_f32_e32 v18, v28, v28
	v_fmac_f32_e32 v19, v30, v30
	v_fmac_f32_e32 v29, v20, v20
	v_fmac_f32_e32 v31, v22, v22
	v_mul_f32_e32 v193, v27, v27
	v_mul_f32_e32 v195, v189, v189
	v_fmac_f32_e32 v192, v24, v24
	v_fmac_f32_e32 v194, v190, v190
	v_add_f32_e32 v18, v18, v19
	v_add_f32_e32 v19, v29, v31
	v_fmac_f32_e32 v193, v26, v26
	v_fmac_f32_e32 v195, v188, v188
	v_add_f32_e32 v18, v192, v18
	v_add_f32_e32 v19, v194, v19
	v_add_f32_e32 v18, v193, v18
	v_add_f32_e32 v19, v195, v19
	v_add_f32_e32 v28, v18, v19
	ds_bpermute_b32 v29, v156, v28
	v_cvt_pk_bf16_f32 v18, v24, v25
	v_cvt_pk_bf16_f32 v19, v26, v27
	global_store_dwordx4 v[42:43], v[16:19], off
	s_waitcnt lgkmcnt(0)
	s_nop 0
	v_add_f32_e32 v16, v28, v29
	ds_bpermute_b32 v17, v155, v16
	v_cvt_pk_bf16_f32 v18, v20, v21
	v_cvt_pk_bf16_f32 v19, v22, v23
	v_cvt_pk_bf16_f32 v20, v190, v191
	v_cvt_pk_bf16_f32 v21, v188, v189
	global_store_dwordx4 v[42:43], v[18:21], off offset:256
	s_and_saveexec_b64 s[20:21], s[2:3]
	s_cbranch_execz .LBB0_1199
	v_lshl_add_u64 v[18:19], v[32:33], 2, s[8:9]
	s_waitcnt lgkmcnt(0)
	v_add_f32_e32 v16, v16, v17
	global_atomic_add_f32 v[18:19], v16, off

.LBB0_1349:
	s_ashr_i32 s15, s14, 31
	v_cmp_lt_i64_e32 vcc, s[16:17], v[140:141]
	s_lshl_b64 s[16:17], s[14:15], 22
	s_add_u32 s16, s68, s16
	s_addc_u32 s17, s69, s17
	s_and_b64 s[18:19], vcc, exec
	s_cselect_b32 s15, s17, s25
	s_cselect_b32 s21, s16, s24
	s_ashr_i32 s13, s12, 31
	s_lshl_b64 s[18:19], s[12:13], 22
	s_add_u32 s18, s31, s18
	s_addc_u32 s19, s33, s19
	s_and_b64 s[28:29], vcc, exec
	s_cselect_b32 s13, s19, s27
	s_cselect_b32 s46, s18, s26
	s_add_u32 s24, s24, 0x200080
	s_addc_u32 s25, s25, 0
	s_add_u32 s47, s26, 0x100
	v_mov_b32_e32 v0, 0
	s_addc_u32 s48, s27, 0
	s_mov_b32 s49, -2
	s_waitcnt lgkmcnt(0)
	v_mov_b32_e32 v1, v0
	v_mov_b32_e32 v2, v0
	v_mov_b32_e32 v3, v0
	v_mov_b32_e32 v4, v0
	v_mov_b32_e32 v5, v0
	v_mov_b32_e32 v6, v0
	v_mov_b32_e32 v7, v0
	v_mov_b32_e32 v16, v0
	v_mov_b32_e32 v17, v0
	v_mov_b32_e32 v18, v0
	v_mov_b32_e32 v19, v0
	v_mov_b32_e32 v20, v0
	v_mov_b32_e32 v21, v0
	v_mov_b32_e32 v22, v0
	v_mov_b32_e32 v23, v0
	v_mov_b32_e32 v32, v0
	v_mov_b32_e32 v33, v0
	v_mov_b32_e32 v34, v0
	v_mov_b32_e32 v35, v0
	v_mov_b32_e32 v36, v0
	v_mov_b32_e32 v37, v0
	v_mov_b32_e32 v38, v0
	v_mov_b32_e32 v39, v0
	v_mov_b32_e32 v48, v0
	v_mov_b32_e32 v49, v0
	v_mov_b32_e32 v50, v0
	v_mov_b32_e32 v51, v0
	v_mov_b32_e32 v52, v0
	v_mov_b32_e32 v53, v0
	v_mov_b32_e32 v54, v0
	v_mov_b32_e32 v55, v0
	v_mov_b32_e32 v8, v0
	v_mov_b32_e32 v9, v0
	v_mov_b32_e32 v10, v0
	v_mov_b32_e32 v11, v0
	v_mov_b32_e32 v12, v0
	v_mov_b32_e32 v13, v0
	v_mov_b32_e32 v14, v0
	v_mov_b32_e32 v15, v0
	v_mov_b32_e32 v24, v0
	v_mov_b32_e32 v25, v0
	v_mov_b32_e32 v26, v0
	v_mov_b32_e32 v27, v0
	v_mov_b32_e32 v28, v0
	v_mov_b32_e32 v29, v0
	v_mov_b32_e32 v30, v0
	v_mov_b32_e32 v31, v0
	v_mov_b32_e32 v40, v0
	v_mov_b32_e32 v41, v0
	v_mov_b32_e32 v42, v0
	v_mov_b32_e32 v43, v0
	v_mov_b32_e32 v44, v0
	v_mov_b32_e32 v45, v0
	v_mov_b32_e32 v46, v0
	v_mov_b32_e32 v47, v0
	v_mov_b32_e32 v56, v0
	v_mov_b32_e32 v57, v0
	v_mov_b32_e32 v58, v0
	v_mov_b32_e32 v59, v0
	v_mov_b32_e32 v60, v0
	v_mov_b32_e32 v61, v0
	v_mov_b32_e32 v62, v0
	v_mov_b32_e32 v63, v0
	v_mov_b32_e32 v64, v0
	v_mov_b32_e32 v65, v0
	v_mov_b32_e32 v66, v0
	v_mov_b32_e32 v67, v0
	v_mov_b32_e32 v68, v0
	v_mov_b32_e32 v69, v0
	v_mov_b32_e32 v70, v0
	v_mov_b32_e32 v71, v0
	v_mov_b32_e32 v80, v0
	v_mov_b32_e32 v81, v0
	v_mov_b32_e32 v82, v0
	v_mov_b32_e32 v83, v0
	v_mov_b32_e32 v84, v0
	v_mov_b32_e32 v85, v0
	v_mov_b32_e32 v86, v0
	v_mov_b32_e32 v87, v0
	v_mov_b32_e32 v96, v0
	v_mov_b32_e32 v97, v0
	v_mov_b32_e32 v98, v0
	v_mov_b32_e32 v99, v0
	v_mov_b32_e32 v100, v0
	v_mov_b32_e32 v101, v0
	v_mov_b32_e32 v102, v0
	v_mov_b32_e32 v103, v0
	v_mov_b32_e32 v112, v0
	v_mov_b32_e32 v113, v0
	v_mov_b32_e32 v114, v0
	v_mov_b32_e32 v115, v0
	v_mov_b32_e32 v116, v0
	v_mov_b32_e32 v117, v0
	v_mov_b32_e32 v118, v0
	v_mov_b32_e32 v119, v0
	v_mov_b32_e32 v72, v0
	v_mov_b32_e32 v73, v0
	v_mov_b32_e32 v74, v0
	v_mov_b32_e32 v75, v0
	v_mov_b32_e32 v76, v0
	v_mov_b32_e32 v77, v0
	v_mov_b32_e32 v78, v0
	v_mov_b32_e32 v79, v0
	v_mov_b32_e32 v88, v0
	v_mov_b32_e32 v89, v0
	v_mov_b32_e32 v90, v0
	v_mov_b32_e32 v91, v0
	v_mov_b32_e32 v92, v0
	v_mov_b32_e32 v93, v0
	v_mov_b32_e32 v94, v0
	v_mov_b32_e32 v95, v0
	v_mov_b32_e32 v104, v0
	v_mov_b32_e32 v105, v0
	v_mov_b32_e32 v106, v0
	v_mov_b32_e32 v107, v0
	v_mov_b32_e32 v108, v0
	v_mov_b32_e32 v109, v0
	v_mov_b32_e32 v110, v0
	v_mov_b32_e32 v111, v0
	v_mov_b32_e32 v120, v0
	v_mov_b32_e32 v121, v0
	v_mov_b32_e32 v122, v0
	v_mov_b32_e32 v123, v0
	v_mov_b32_e32 v124, v0
	v_mov_b32_e32 v125, v0
	v_mov_b32_e32 v126, v0
	v_mov_b32_e32 v127, v0
	v_lshl_add_u32 v254, s20, 8, v148
	v_lshl_or_b32 v255, s22, 8, v150
	v_lshlrev_b32_e32 v254, 12, v254
	v_lshl_add_u32 v254, v255, 1, v254
	global_load_dwordx4 v[236:239], v254, s[6:7]
	global_load_dwordx4 v[240:243], v254, s[6:7] offset:256
	s_add_u32 s98, s6, 0x10000
	s_addc_u32 s99, s7, 0
	global_load_dwordx4 v[244:247], v254, s[98:99]
	global_load_dwordx4 v[248:251], v254, s[98:99] offset:256
.LBB0_1350:
	ds_read_b128 v[144:147], v151
	ds_read_b128 v[156:159], v151 offset:1024
	ds_read_b128 v[160:163], v151 offset:2048
	ds_read_b128 v[164:167], v151 offset:3072
	s_add_u32 s26, s24, 0xffe00080
	s_addc_u32 s27, s25, -1
	s_cmpk_eq_i32 s49, 0x7c
	s_cselect_b32 s29, s15, s27
	s_cselect_b32 s28, s21, s26
	s_cselect_b32 s27, s13, s48
	s_cselect_b32 s26, s46, s47
	v_lshl_add_u64 v[168:169], s[24:25], 0, v[136:137]
	s_add_i32 m0, s23, 0xc000
	ds_read_b128 v[172:175], v152
	ds_read_b128 v[176:179], v152 offset:1024
	ds_read_b128 v[180:183], v152 offset:2048
	ds_read_b128 v[184:187], v152 offset:3072
	ds_read_b128 v[188:191], v152 offset:4096
	ds_read_b128 v[192:195], v152 offset:5120
	ds_read_b128 v[196:199], v152 offset:6144
	ds_read_b128 v[200:203], v152 offset:7168
	global_load_lds_dwordx4 v[168:169], off
	v_lshl_add_u64 v[168:169], s[24:25], 0, v[138:139]
	s_add_i32 m0, s23, 0xe000
	s_nop 0
	global_load_lds_dwordx4 v[168:169], off
	s_waitcnt lgkmcnt(8)
	s_barrier
	s_waitcnt lgkmcnt(0)
	s_setprio 1
	s_waitcnt lgkmcnt(0)
	v_mfma_f32_16x16x32_bf16 v[124:127], v[144:147], v[172:175], v[124:127]
	v_mfma_f32_16x16x32_bf16 v[120:123], v[160:163], v[172:175], v[120:123]
	v_mfma_f32_16x16x32_bf16 v[108:111], v[144:147], v[180:183], v[108:111]
	v_mfma_f32_16x16x32_bf16 v[104:107], v[160:163], v[180:183], v[104:107]
	v_mfma_f32_16x16x32_bf16 v[92:95], v[144:147], v[188:191], v[92:95]
	v_mfma_f32_16x16x32_bf16 v[88:91], v[160:163], v[188:191], v[88:91]
	v_mfma_f32_16x16x32_bf16 v[76:79], v[144:147], v[196:199], v[76:79]
	v_mfma_f32_16x16x32_bf16 v[72:75], v[160:163], v[196:199], v[72:75]
	v_mfma_f32_16x16x32_bf16 v[124:127], v[156:159], v[176:179], v[124:127]
	v_mfma_f32_16x16x32_bf16 v[120:123], v[164:167], v[176:179], v[120:123]
	v_mfma_f32_16x16x32_bf16 v[108:111], v[156:159], v[184:187], v[108:111]
	v_mfma_f32_16x16x32_bf16 v[104:107], v[164:167], v[184:187], v[104:107]
	v_mfma_f32_16x16x32_bf16 v[92:95], v[156:159], v[192:195], v[92:95]
	v_mfma_f32_16x16x32_bf16 v[88:91], v[164:167], v[192:195], v[88:91]
	v_mfma_f32_16x16x32_bf16 v[76:79], v[156:159], v[200:203], v[76:79]
	v_mfma_f32_16x16x32_bf16 v[72:75], v[164:167], v[200:203], v[72:75]
	s_setprio 0
	s_barrier
	s_add_i32 s50, s44, s34
	v_lshl_add_u64 v[168:169], s[26:27], 0, v[130:131]
	s_mov_b32 m0, s50
	ds_read_b128 v[204:207], v153
	ds_read_b128 v[208:211], v153 offset:1024
	ds_read_b128 v[212:215], v153 offset:2048
	ds_read_b128 v[216:219], v153 offset:3072
	global_load_lds_dwordx4 v[168:169], off
	v_lshl_add_u64 v[220:221], s[26:27], 0, v[134:135]
	s_add_i32 m0, s50, 0x2000
	s_nop 0
	global_load_lds_dwordx4 v[220:221], off
	s_barrier
	s_waitcnt lgkmcnt(0)
	s_setprio 1
	s_waitcnt lgkmcnt(0)
	v_mfma_f32_16x16x32_bf16 v[116:119], v[204:207], v[172:175], v[116:119]
	v_mfma_f32_16x16x32_bf16 v[112:115], v[212:215], v[172:175], v[112:115]
	v_mfma_f32_16x16x32_bf16 v[100:103], v[204:207], v[180:183], v[100:103]
	v_mfma_f32_16x16x32_bf16 v[96:99], v[212:215], v[180:183], v[96:99]
	v_mfma_f32_16x16x32_bf16 v[84:87], v[204:207], v[188:191], v[84:87]
	v_mfma_f32_16x16x32_bf16 v[80:83], v[212:215], v[188:191], v[80:83]
	v_mfma_f32_16x16x32_bf16 v[68:71], v[204:207], v[196:199], v[68:71]
	v_mfma_f32_16x16x32_bf16 v[64:67], v[212:215], v[196:199], v[64:67]
	v_mfma_f32_16x16x32_bf16 v[116:119], v[208:211], v[176:179], v[116:119]
	v_mfma_f32_16x16x32_bf16 v[112:115], v[216:219], v[176:179], v[112:115]
	v_mfma_f32_16x16x32_bf16 v[100:103], v[208:211], v[184:187], v[100:103]
	v_mfma_f32_16x16x32_bf16 v[96:99], v[216:219], v[184:187], v[96:99]
	v_mfma_f32_16x16x32_bf16 v[84:87], v[208:211], v[192:195], v[84:87]
	v_mfma_f32_16x16x32_bf16 v[80:83], v[216:219], v[192:195], v[80:83]
	v_mfma_f32_16x16x32_bf16 v[68:71], v[208:211], v[200:203], v[68:71]
	v_mfma_f32_16x16x32_bf16 v[64:67], v[216:219], v[200:203], v[64:67]
	s_setprio 0
	s_mov_b32 m0, s23
	v_lshl_add_u64 v[222:223], s[28:29], 0, v[128:129]
	s_barrier
	ds_read_b128 v[172:175], v152 offset:16384
	ds_read_b128 v[176:179], v152 offset:17408
	ds_read_b128 v[180:183], v152 offset:18432
	ds_read_b128 v[184:187], v152 offset:19456
	ds_read_b128 v[188:191], v152 offset:20480
	ds_read_b128 v[192:195], v152 offset:21504
	ds_read_b128 v[196:199], v152 offset:22528
	ds_read_b128 v[200:203], v152 offset:23552
	global_load_lds_dwordx4 v[222:223], off
	v_lshl_add_u64 v[224:225], s[28:29], 0, v[132:133]
	s_mov_b32 m0, s35
	s_nop 0
	global_load_lds_dwordx4 v[224:225], off
	s_barrier
	s_waitcnt lgkmcnt(0)
	s_setprio 1
	s_waitcnt lgkmcnt(0)
	v_mfma_f32_16x16x32_bf16 v[60:63], v[144:147], v[172:175], v[60:63]
	v_mfma_f32_16x16x32_bf16 v[56:59], v[160:163], v[172:175], v[56:59]
	v_mfma_f32_16x16x32_bf16 v[44:47], v[144:147], v[180:183], v[44:47]
	v_mfma_f32_16x16x32_bf16 v[40:43], v[160:163], v[180:183], v[40:43]
	v_mfma_f32_16x16x32_bf16 v[28:31], v[144:147], v[188:191], v[28:31]
	v_mfma_f32_16x16x32_bf16 v[24:27], v[160:163], v[188:191], v[24:27]
	v_mfma_f32_16x16x32_bf16 v[12:15], v[144:147], v[196:199], v[12:15]
	v_mfma_f32_16x16x32_bf16 v[8:11], v[160:163], v[196:199], v[8:11]
	v_mfma_f32_16x16x32_bf16 v[60:63], v[156:159], v[176:179], v[60:63]
	v_mfma_f32_16x16x32_bf16 v[56:59], v[164:167], v[176:179], v[56:59]
	v_mfma_f32_16x16x32_bf16 v[44:47], v[156:159], v[184:187], v[44:47]
	v_mfma_f32_16x16x32_bf16 v[40:43], v[164:167], v[184:187], v[40:43]
	v_mfma_f32_16x16x32_bf16 v[28:31], v[156:159], v[192:195], v[28:31]
	v_mfma_f32_16x16x32_bf16 v[24:27], v[164:167], v[192:195], v[24:27]
	v_mfma_f32_16x16x32_bf16 v[12:15], v[156:159], v[200:203], v[12:15]
	v_mfma_f32_16x16x32_bf16 v[8:11], v[164:167], v[200:203], v[8:11]
	s_setprio 0
	s_barrier
	s_add_u32 s50, s26, 0x200000
	s_addc_u32 s51, s27, 0
	s_add_i32 s52, s45, s34
	v_lshl_add_u64 v[144:145], s[50:51], 0, v[130:131]
	s_mov_b32 m0, s52
	s_nop 0
	global_load_lds_dwordx4 v[144:145], off
	v_lshl_add_u64 v[144:145], s[50:51], 0, v[134:135]
	s_add_i32 m0, s52, 0x2000
	s_nop 0
	global_load_lds_dwordx4 v[144:145], off
	s_waitcnt vmcnt(6)
	s_barrier
	s_setprio 1
	v_mfma_f32_16x16x32_bf16 v[52:55], v[204:207], v[172:175], v[52:55]
	v_mfma_f32_16x16x32_bf16 v[48:51], v[212:215], v[172:175], v[48:51]
	v_mfma_f32_16x16x32_bf16 v[36:39], v[204:207], v[180:183], v[36:39]
	v_mfma_f32_16x16x32_bf16 v[32:35], v[212:215], v[180:183], v[32:35]
	v_mfma_f32_16x16x32_bf16 v[20:23], v[204:207], v[188:191], v[20:23]
	v_mfma_f32_16x16x32_bf16 v[16:19], v[212:215], v[188:191], v[16:19]
	v_mfma_f32_16x16x32_bf16 v[4:7], v[204:207], v[196:199], v[4:7]
	v_mfma_f32_16x16x32_bf16 v[0:3], v[212:215], v[196:199], v[0:3]
	v_mfma_f32_16x16x32_bf16 v[52:55], v[208:211], v[176:179], v[52:55]
	v_mfma_f32_16x16x32_bf16 v[48:51], v[216:219], v[176:179], v[48:51]
	v_mfma_f32_16x16x32_bf16 v[36:39], v[208:211], v[184:187], v[36:39]
	v_mfma_f32_16x16x32_bf16 v[32:35], v[216:219], v[184:187], v[32:35]
	v_mfma_f32_16x16x32_bf16 v[20:23], v[208:211], v[192:195], v[20:23]
	v_mfma_f32_16x16x32_bf16 v[16:19], v[216:219], v[192:195], v[16:19]
	v_mfma_f32_16x16x32_bf16 v[4:7], v[208:211], v[200:203], v[4:7]
	v_mfma_f32_16x16x32_bf16 v[0:3], v[216:219], v[200:203], v[0:3]
	s_setprio 0
	s_add_i32 s50, 0, 0x18000
	v_add_u32_e32 v155, s50, v149
	s_barrier
	ds_read_b128 v[144:147], v155
	ds_read_b128 v[156:159], v155 offset:1024
	ds_read_b128 v[160:163], v155 offset:2048
	ds_read_b128 v[164:167], v155 offset:3072
	s_add_u32 s28, s28, 0x200000
	s_addc_u32 s29, s29, 0
	s_mov_b32 m0, s36
	v_lshl_add_u64 v[204:205], s[28:29], 0, v[128:129]
	ds_read_b128 v[172:175], v152 offset:32768
	ds_read_b128 v[176:179], v152 offset:33792
	ds_read_b128 v[180:183], v152 offset:34816
	ds_read_b128 v[184:187], v152 offset:35840
	ds_read_b128 v[188:191], v152 offset:36864
	ds_read_b128 v[192:195], v152 offset:37888
	ds_read_b128 v[196:199], v152 offset:38912
	ds_read_b128 v[200:203], v152 offset:39936
	global_load_lds_dwordx4 v[204:205], off
	v_lshl_add_u64 v[204:205], s[28:29], 0, v[132:133]
	s_mov_b32 m0, s37
	s_nop 0
	global_load_lds_dwordx4 v[204:205], off
	s_waitcnt lgkmcnt(8)
	s_barrier
	s_waitcnt lgkmcnt(0)
	s_setprio 1
	s_waitcnt lgkmcnt(0)
	v_mfma_f32_16x16x32_bf16 v[124:127], v[144:147], v[172:175], v[124:127]
	v_mfma_f32_16x16x32_bf16 v[120:123], v[160:163], v[172:175], v[120:123]
	v_mfma_f32_16x16x32_bf16 v[108:111], v[144:147], v[180:183], v[108:111]
	v_mfma_f32_16x16x32_bf16 v[104:107], v[160:163], v[180:183], v[104:107]
	v_mfma_f32_16x16x32_bf16 v[92:95], v[144:147], v[188:191], v[92:95]
	v_mfma_f32_16x16x32_bf16 v[88:91], v[160:163], v[188:191], v[88:91]
	v_mfma_f32_16x16x32_bf16 v[76:79], v[144:147], v[196:199], v[76:79]
	v_mfma_f32_16x16x32_bf16 v[72:75], v[160:163], v[196:199], v[72:75]
	v_mfma_f32_16x16x32_bf16 v[124:127], v[156:159], v[176:179], v[124:127]
	v_mfma_f32_16x16x32_bf16 v[120:123], v[164:167], v[176:179], v[120:123]
	v_mfma_f32_16x16x32_bf16 v[108:111], v[156:159], v[184:187], v[108:111]
	v_mfma_f32_16x16x32_bf16 v[104:107], v[164:167], v[184:187], v[104:107]
	v_mfma_f32_16x16x32_bf16 v[92:95], v[156:159], v[192:195], v[92:95]
	v_mfma_f32_16x16x32_bf16 v[88:91], v[164:167], v[192:195], v[88:91]
	v_mfma_f32_16x16x32_bf16 v[76:79], v[156:159], v[200:203], v[76:79]
	v_mfma_f32_16x16x32_bf16 v[72:75], v[164:167], v[200:203], v[72:75]
	s_setprio 0
	s_barrier
	s_add_i32 s28, 0, 0x1c000
	s_add_i32 s29, s50, s34
	v_add_u32_e32 v155, s28, v149
	v_lshl_add_u64 v[168:169], v[168:169], 0, s[10:11]
	s_mov_b32 m0, s29
	ds_read_b128 v[204:207], v155
	ds_read_b128 v[208:211], v155 offset:1024
	ds_read_b128 v[212:215], v155 offset:2048
	ds_read_b128 v[216:219], v155 offset:3072
	global_load_lds_dwordx4 v[168:169], off
	v_lshl_add_u64 v[168:169], v[220:221], 0, s[10:11]
	s_add_i32 m0, s29, 0x2000
	s_nop 0
	global_load_lds_dwordx4 v[168:169], off
	s_barrier
	s_waitcnt lgkmcnt(0)
	s_setprio 1
	s_waitcnt lgkmcnt(0)
	v_mfma_f32_16x16x32_bf16 v[116:119], v[204:207], v[172:175], v[116:119]
	v_mfma_f32_16x16x32_bf16 v[112:115], v[212:215], v[172:175], v[112:115]
	v_mfma_f32_16x16x32_bf16 v[100:103], v[204:207], v[180:183], v[100:103]
	v_mfma_f32_16x16x32_bf16 v[96:99], v[212:215], v[180:183], v[96:99]
	v_mfma_f32_16x16x32_bf16 v[84:87], v[204:207], v[188:191], v[84:87]
	v_mfma_f32_16x16x32_bf16 v[80:83], v[212:215], v[188:191], v[80:83]
	v_mfma_f32_16x16x32_bf16 v[68:71], v[204:207], v[196:199], v[68:71]
	v_mfma_f32_16x16x32_bf16 v[64:67], v[212:215], v[196:199], v[64:67]
	v_mfma_f32_16x16x32_bf16 v[116:119], v[208:211], v[176:179], v[116:119]
	v_mfma_f32_16x16x32_bf16 v[112:115], v[216:219], v[176:179], v[112:115]
	v_mfma_f32_16x16x32_bf16 v[100:103], v[208:211], v[184:187], v[100:103]
	v_mfma_f32_16x16x32_bf16 v[96:99], v[216:219], v[184:187], v[96:99]
	v_mfma_f32_16x16x32_bf16 v[84:87], v[208:211], v[192:195], v[84:87]
	v_mfma_f32_16x16x32_bf16 v[80:83], v[216:219], v[192:195], v[80:83]
	v_mfma_f32_16x16x32_bf16 v[68:71], v[208:211], v[200:203], v[68:71]
	v_mfma_f32_16x16x32_bf16 v[64:67], v[216:219], v[200:203], v[64:67]
	s_setprio 0
	s_mov_b32 m0, s39
	v_lshl_add_u64 v[168:169], v[222:223], 0, s[10:11]
	s_barrier
	ds_read_b128 v[172:175], v152 offset:49152
	ds_read_b128 v[176:179], v152 offset:50176
	ds_read_b128 v[180:183], v152 offset:51200
	ds_read_b128 v[184:187], v152 offset:52224
	ds_read_b128 v[188:191], v152 offset:53248
	ds_read_b128 v[192:195], v152 offset:54272
	ds_read_b128 v[196:199], v152 offset:55296
	ds_read_b128 v[200:203], v152 offset:56320
	global_load_lds_dwordx4 v[168:169], off
	v_lshl_add_u64 v[168:169], v[224:225], 0, s[10:11]
	s_mov_b32 m0, s40
	s_nop 0
	global_load_lds_dwordx4 v[168:169], off
	s_barrier
	s_waitcnt lgkmcnt(0)
	s_setprio 1
	s_waitcnt lgkmcnt(0)
	v_mfma_f32_16x16x32_bf16 v[60:63], v[144:147], v[172:175], v[60:63]
	v_mfma_f32_16x16x32_bf16 v[56:59], v[160:163], v[172:175], v[56:59]
	v_mfma_f32_16x16x32_bf16 v[44:47], v[144:147], v[180:183], v[44:47]
	v_mfma_f32_16x16x32_bf16 v[40:43], v[160:163], v[180:183], v[40:43]
	v_mfma_f32_16x16x32_bf16 v[28:31], v[144:147], v[188:191], v[28:31]
	v_mfma_f32_16x16x32_bf16 v[24:27], v[160:163], v[188:191], v[24:27]
	v_mfma_f32_16x16x32_bf16 v[12:15], v[144:147], v[196:199], v[12:15]
	v_mfma_f32_16x16x32_bf16 v[8:11], v[160:163], v[196:199], v[8:11]
	v_mfma_f32_16x16x32_bf16 v[60:63], v[156:159], v[176:179], v[60:63]
	v_mfma_f32_16x16x32_bf16 v[56:59], v[164:167], v[176:179], v[56:59]
	v_mfma_f32_16x16x32_bf16 v[44:47], v[156:159], v[184:187], v[44:47]
	v_mfma_f32_16x16x32_bf16 v[40:43], v[164:167], v[184:187], v[40:43]
	v_mfma_f32_16x16x32_bf16 v[28:31], v[156:159], v[192:195], v[28:31]
	v_mfma_f32_16x16x32_bf16 v[24:27], v[164:167], v[192:195], v[24:27]
	v_mfma_f32_16x16x32_bf16 v[12:15], v[156:159], v[200:203], v[12:15]
	v_mfma_f32_16x16x32_bf16 v[8:11], v[164:167], v[200:203], v[8:11]
	s_setprio 0
	s_barrier
	s_add_u32 s26, s26, 0x200080
	s_addc_u32 s27, s27, 0
	s_add_i32 s28, s28, s34
	v_lshl_add_u64 v[144:145], s[26:27], 0, v[130:131]
	s_mov_b32 m0, s28
	s_nop 0
	global_load_lds_dwordx4 v[144:145], off
	v_lshl_add_u64 v[144:145], s[26:27], 0, v[134:135]
	s_add_i32 m0, s28, 0x2000
	s_nop 0
	global_load_lds_dwordx4 v[144:145], off
	s_waitcnt vmcnt(6)
	s_barrier
	s_setprio 1
	v_mfma_f32_16x16x32_bf16 v[52:55], v[204:207], v[172:175], v[52:55]
	v_mfma_f32_16x16x32_bf16 v[48:51], v[212:215], v[172:175], v[48:51]
	v_mfma_f32_16x16x32_bf16 v[36:39], v[204:207], v[180:183], v[36:39]
	v_mfma_f32_16x16x32_bf16 v[32:35], v[212:215], v[180:183], v[32:35]
	v_mfma_f32_16x16x32_bf16 v[20:23], v[204:207], v[188:191], v[20:23]
	v_mfma_f32_16x16x32_bf16 v[16:19], v[212:215], v[188:191], v[16:19]
	v_mfma_f32_16x16x32_bf16 v[4:7], v[204:207], v[196:199], v[4:7]
	v_mfma_f32_16x16x32_bf16 v[0:3], v[212:215], v[196:199], v[0:3]
	v_mfma_f32_16x16x32_bf16 v[52:55], v[208:211], v[176:179], v[52:55]
	v_mfma_f32_16x16x32_bf16 v[48:51], v[216:219], v[176:179], v[48:51]
	v_mfma_f32_16x16x32_bf16 v[36:39], v[208:211], v[184:187], v[36:39]
	v_mfma_f32_16x16x32_bf16 v[32:35], v[216:219], v[184:187], v[32:35]
	v_mfma_f32_16x16x32_bf16 v[20:23], v[208:211], v[192:195], v[20:23]
	v_mfma_f32_16x16x32_bf16 v[16:19], v[216:219], v[192:195], v[16:19]
	v_mfma_f32_16x16x32_bf16 v[4:7], v[208:211], v[200:203], v[4:7]
	v_mfma_f32_16x16x32_bf16 v[0:3], v[216:219], v[200:203], v[0:3]
	s_setprio 0
	s_add_i32 s49, s49, 2
	s_add_u32 s24, s24, 0x100
	s_addc_u32 s25, s25, 0
	s_add_u32 s47, s47, 0x100
	s_addc_u32 s48, s48, 0
	s_cmpk_gt_u32 s49, 0x7d
	s_barrier
	s_cbranch_scc0 .LBB0_1350
	v_lshl_add_u32 v146, s20, 8, v148
	v_ashrrev_i32_e32 v147, 31, v146
	v_lshl_or_b32 v144, s22, 8, v150
	v_lshlrev_b32_e32 v179, 12, v146
	v_lshl_add_u32 v178, v144, 1, v179
	s_add_u32 s98, s6, 0x20000
	s_addc_u32 s99, s7, 0
	global_load_dwordx4 v[196:199], v178, s[98:99]
	global_load_dwordx4 v[200:203], v178, s[98:99] offset:256
	s_add_u32 s98, s6, 0x30000
	s_addc_u32 s99, s7, 0
	global_load_dwordx4 v[204:207], v178, s[98:99]
	global_load_dwordx4 v[208:211], v178, s[98:99] offset:256
	s_add_u32 s98, s6, 0x80000
	s_addc_u32 s99, s7, 0
	global_load_dwordx4 v[212:215], v178, s[98:99]
	global_load_dwordx4 v[216:219], v178, s[98:99] offset:256
	s_add_u32 s98, s6, 0x90000
	s_addc_u32 s99, s7, 0
	global_load_dwordx4 v[180:183], v178, s[98:99]
	global_load_dwordx4 v[184:187], v178, s[98:99] offset:256
	s_add_u32 s98, s6, 0xa0000
	s_addc_u32 s99, s7, 0
	global_load_dwordx4 v[188:191], v178, s[98:99]
	global_load_dwordx4 v[192:195], v178, s[98:99] offset:256
	s_add_u32 s98, s6, 0xb0000
	s_addc_u32 s99, s7, 0
	global_load_dwordx4 v[220:223], v178, s[98:99]
	global_load_dwordx4 v[252:255], v178, s[98:99] offset:256
	v_lshlrev_b64 v[156:157], 12, v[146:147]
	v_ashrrev_i32_e32 v145, 31, v144
	v_lshl_add_u64 v[156:157], s[6:7], 0, v[156:157]
	v_lshl_add_u64 v[166:167], v[144:145], 1, v[156:157]
	v_and_b32_e32 v156, 64, v154
	v_xor_b32_e32 v155, 16, v154
	v_add_u32_e32 v156, 64, v156
	v_xor_b32_e32 v157, 32, v154
	v_cmp_lt_i32_e32 vcc, v155, v156
	s_waitcnt vmcnt(12)
	v_lshlrev_b32_e32 v168, 16, v236
	v_and_b32_e32 v169, 0xffff0000, v236
	v_lshlrev_b32_e32 v236, 16, v237
	v_and_b32_e32 v237, 0xffff0000, v237
	v_lshlrev_b32_e32 v174, 16, v240
	v_and_b32_e32 v175, 0xffff0000, v240
	v_lshlrev_b32_e32 v240, 16, v241
	v_and_b32_e32 v241, 0xffff0000, v241
	v_cndmask_b32_e32 v155, v154, v155, vcc
	v_cmp_lt_i32_e32 vcc, v157, v156
	v_lshlrev_b32_e32 v172, 16, v238
	v_and_b32_e32 v173, 0xffff0000, v238
	v_lshlrev_b32_e32 v238, 16, v239
	v_and_b32_e32 v239, 0xffff0000, v239
	v_lshlrev_b32_e32 v176, 16, v242
	v_and_b32_e32 v177, 0xffff0000, v242
	v_lshlrev_b32_e32 v242, 16, v243
	v_and_b32_e32 v243, 0xffff0000, v243
	v_pk_add_f32 v[126:127], v[126:127], v[236:237]
	v_pk_add_f32 v[124:125], v[124:125], v[168:169]
	v_pk_add_f32 v[118:119], v[118:119], v[240:241]
	v_pk_add_f32 v[116:117], v[116:117], v[174:175]
	v_cndmask_b32_e32 v157, v154, v157, vcc
	v_pk_add_f32 v[122:123], v[122:123], v[238:239]
	v_pk_add_f32 v[120:121], v[120:121], v[172:173]
	v_pk_add_f32 v[236:237], v[114:115], v[242:243]
	v_pk_add_f32 v[238:239], v[112:113], v[176:177]
	v_mul_f32_e32 v114, v125, v125
	v_mul_f32_e32 v115, v127, v127
	v_cvt_pk_bf16_f32 v112, v124, v125
	v_cvt_pk_bf16_f32 v113, v126, v127
	v_mul_f32_e32 v125, v117, v117
	v_mul_f32_e32 v127, v119, v119
	v_lshlrev_b32_e32 v156, 2, v155
	v_lshlrev_b32_e32 v155, 2, v157
	v_mul_f32_e32 v157, v121, v121
	v_mul_f32_e32 v241, v239, v239
	v_fmac_f32_e32 v114, v124, v124
	v_fmac_f32_e32 v115, v126, v126
	v_fmac_f32_e32 v125, v116, v116
	v_fmac_f32_e32 v127, v118, v118
	v_mul_f32_e32 v240, v123, v123
	v_mul_f32_e32 v242, v237, v237
	v_fmac_f32_e32 v157, v120, v120
	v_fmac_f32_e32 v241, v238, v238
	v_add_f32_e32 v114, v114, v115
	v_add_f32_e32 v115, v125, v127
	v_fmac_f32_e32 v240, v122, v122
	v_fmac_f32_e32 v242, v236, v236
	v_add_f32_e32 v114, v157, v114
	v_add_f32_e32 v115, v241, v115
	v_add_f32_e32 v114, v240, v114
	v_add_f32_e32 v115, v242, v115
	v_add_f32_e32 v124, v114, v115
	ds_bpermute_b32 v125, v156, v124
	v_cvt_pk_bf16_f32 v114, v120, v121
	v_cvt_pk_bf16_f32 v115, v122, v123
	global_store_dwordx4 v[166:167], v[112:115], off
	s_waitcnt lgkmcnt(0)
	s_nop 0
	v_add_f32_e32 v112, v124, v125
	ds_bpermute_b32 v113, v155, v112
	v_cvt_pk_bf16_f32 v114, v116, v117
	v_cvt_pk_bf16_f32 v115, v118, v119
	v_cvt_pk_bf16_f32 v116, v238, v239
	v_cvt_pk_bf16_f32 v117, v236, v237
	global_store_dwordx4 v[166:167], v[114:117], off offset:256
	s_and_saveexec_b64 s[20:21], s[2:3]
	s_cbranch_execz .LBB0_1353
	v_lshl_add_u64 v[114:115], v[146:147], 2, s[8:9]
	s_waitcnt lgkmcnt(0)
	v_add_f32_e32 v112, v112, v113
	global_atomic_add_f32 v[114:115], v112, off
